# GEMM steps: one static s_setprio 1 for waves 4-7 (the lagging half) at step entry, reset at step end; no per-phase flips
# baseline (speedup 1.0000x reference)
.LBB0_54:
	s_add_i32 m0, s28, 0x18000
	v_lshl_add_u64 v[0:1], v[0:1], 0, s[70:71]
	s_waitcnt vmcnt(2)
	s_barrier
	global_load_lds_dwordx4 v[0:1], off
	v_lshl_add_u64 v[0:1], v[2:3], 0, s[70:71]
	s_add_i32 m0, s28, 0x1a000
	s_add_i32 s81, s28, 0x8000
	global_load_lds_dwordx4 v[0:1], off
	v_lshl_add_u64 v[0:1], v[8:9], 0, s[70:71]
	s_mov_b32 m0, s81
	s_add_i32 s82, s28, 0xa000
	global_load_lds_dwordx4 v[0:1], off
	v_lshl_add_u64 v[0:1], v[10:11], 0, s[70:71]
	s_mov_b32 m0, s82
	v_bfe_u32 v20, v13, 4, 2
	global_load_lds_dwordx4 v[0:1], off
	s_add_i32 m0, s28, 0x1c000
	v_lshl_add_u64 v[0:1], v[4:5], 0, s[70:71]
	global_load_lds_dwordx4 v[0:1], off
	v_lshl_add_u64 v[0:1], v[6:7], 0, s[70:71]
	s_add_i32 m0, s28, 0x1e000
	v_and_b32_e32 v184, 15, v13
	global_load_lds_dwordx4 v[0:1], off
	v_rcp_iflag_f32_e32 v0, v12
	v_lshlrev_b32_e32 v22, 4, v20
	v_lshlrev_b32_e32 v23, 2, v13
	s_xor_b64 s[64:65], s[0:1], -1
	v_mul_f32_e32 v0, 0x4f7ffffe, v0
	v_cvt_u32_f32_e32 v0, v0
	s_and_b32 s77, s5, 3
	s_lshr_b32 s78, s3, 6
	v_lshl_or_b32 v22, v184, 6, v22
	s_lshl_b32 s0, s19, 13
	v_and_b32_e32 v23, 32, v23
	s_lshl_b32 s79, s19, 6
	v_bitop3_b32 v24, v22, s0, v23 bitop3:0xde
	s_lshl_b32 s0, s77, 12
	s_add_i32 s84, s78, -2
	s_cmpk_lt_u32 s2, 0x100
	v_bitop3_b32 v185, v22, s0, v23 bitop3:0xde
	s_cselect_b64 s[66:67], -1, 0
	s_lshr_b32 s0, s24, 4
	v_readfirstlane_b32 s1, v0
	v_add_u32_e32 v0, v16, v14
	v_writelane_b32 v245, s0, 36
	s_sub_i32 s0, 0, s25
	v_add_lshl_u32 v0, v0, v15, 1
	v_mov_b32_e32 v1, v193
	s_waitcnt vmcnt(6)
	s_mul_i32 s0, s0, s1
	v_lshl_add_u64 v[162:163], s[30:31], 0, v[0:1]
	v_add_u32_e32 v0, v19, v17
	v_lshlrev_b32_e32 v21, 3, v20
	s_mul_hi_u32 s0, s1, s0
	v_add_lshl_u32 v0, v0, v18, 1
	v_lshl_or_b32 v186, s77, 5, v21
	v_and_b32_e32 v187, 63, v13
	s_mov_b32 s85, 0
	v_cmp_eq_u32_e64 s[36:37], 0, v20
	s_mov_b32 s19, s4
	s_add_i32 s2, s1, s0
	v_lshl_add_u64 v[164:165], s[30:31], 0, v[0:1]
	v_add_u32_e32 v188, 0, v24
	v_readfirstlane_b32 s33, v195
	s_nop 3
	s_lshr_b32 s33, s33, 6
	s_cmp_ge_u32 s33, 4
	s_cbranch_scc0 .Lmy_prio_done
	s_setprio 1
.Lmy_prio_done:
	s_barrier
	s_branch .LBB0_57

.LBB0_374:
	s_setprio 0
	v_readlane_b32 s8, v246, 37
	v_readlane_b32 s14, v246, 43
	v_readlane_b32 s9, v246, 38
	v_readlane_b32 s10, v246, 39
	v_readlane_b32 s11, v246, 40
	v_readlane_b32 s12, v246, 41
	v_readlane_b32 s13, v246, 42
	v_readlane_b32 s15, v246, 44
	s_add_i32 s14, s14, 1
	v_writelane_b32 v246, s8, 37
	s_cmp_ge_i32 s14, s15
	s_mov_b64 s[0:1], -1
	v_writelane_b32 v246, s9, 38
	v_writelane_b32 v246, s10, 39
	v_writelane_b32 v246, s11, 40
	v_writelane_b32 v246, s12, 41
	v_writelane_b32 v246, s13, 42
	v_writelane_b32 v246, s14, 43
	s_movk_i32 s5, 0x7fff
	v_writelane_b32 v246, s15, 44
	s_cbranch_scc1 .LBB0_21
	s_waitcnt vmcnt(0)
	s_waitcnt vmcnt(0) lgkmcnt(0)
	s_barrier
	s_mov_b64 s[0:1], exec
	v_readlane_b32 s2, v247, 3
	v_readlane_b32 s3, v247, 4
	s_and_b64 s[2:3], s[0:1], s[2:3]
	s_mov_b64 exec, s[2:3]
	s_cbranch_execz .LBB0_20
	v_readlane_b32 s2, v248, 2
	s_waitcnt vmcnt(0) expcnt(0) lgkmcnt(0)
	s_nop 1
	v_mov_b32_e32 v2, s2
	v_readlane_b32 s3, v248, 3
	s_nop 1
	v_cmp_ne_u32_e32 vcc, 0, v2
	v_mov_b32_e32 v0, s3
	s_cbranch_vccnz .LBB0_391
	s_mov_b32 s5, 1
	s_branch .LBB0_379
